# third XCD-local barrier (phase 3->4) with the segment scan mapped to the XCD that owns the states
# baseline (speedup 1.0000x reference)
.LBB0_258:
	s_cmp_gt_i32 s54, 3
	s_cselect_b64 s[6:7], -1, 0
	s_cmp_lt_i32 s55, 4
	s_cselect_b64 s[8:9], -1, 0
	s_or_b64 s[6:7], s[6:7], s[8:9]
	s_and_b64 vcc, exec, s[6:7]
	v_lshl_add_u32 v144, s2, 8, v168
	s_cbranch_vccnz .LBB0_329
	s_load_dwordx4 s[8:11], s[0:1], 0x78
	s_load_dwordx4 s[12:15], s[0:1], 0xc8
	s_mov_b32 s90, s2
	s_cmp_eq_u32 s52, 0x200
	s_cbranch_scc0 .Lp3_nomap
	s_and_b32 s90, s2, 7
	s_lshr_b32 s91, s2, 3
	s_lshl_b32 s90, s90, 1
	s_lshr_b32 s92, s91, 5
	s_add_u32 s90, s90, s92
	s_and_b32 s91, s91, 31
	s_lshl_b32 s90, s90, 5
	s_or_b32 s90, s90, s91
.Lp3_nomap:
	v_lshl_add_u32 v8, s90, 8, v168
	s_mov_b32 s3, 0x20000
	v_cmp_gt_i32_e32 vcc, s3, v8
	s_and_saveexec_b64 s[6:7], vcc
	s_cbranch_execz .LBB0_264
	s_load_dwordx2 s[16:17], s[0:1], 0x108
	s_waitcnt lgkmcnt(0)
	s_load_dwordx2 s[18:19], s[0:1], 0x118
	s_lshl_b32 s26, s52, 8
	s_lshl_b32 s27, s52, 10
	v_lshlrev_b32_e32 v0, 2, v168
	v_lshl_add_u32 v9, s2, 10, v0
	s_waitcnt lgkmcnt(0)
	s_add_u32 s18, s18, 0x60c
	s_addc_u32 s19, s19, 0
	s_mov_b64 s[20:21], 0
	s_mov_b32 s28, 0x1fff0
	s_movk_i32 s29, 0x1f0
	s_mov_b32 s30, 0x40000
	s_mov_b32 s31, 0x60000
	s_mov_b64 s[22:23], 0x800
	s_mov_b32 s34, 0x1ffff

.LBB0_275:
	s_cmp_lt_i32 s55, 5
	s_cbranch_scc1 .LBB0_329
	s_waitcnt vmcnt(0) lgkmcnt(0)
	s_barrier
	v_mov_b32_e32 v0, 8
	ds_read_b32 v1, v0
	s_waitcnt lgkmcnt(0)
	v_readfirstlane_b32 s3, v1
	s_nop 3
	s_barrier
	s_cmp_lg_u32 s3, 0
	s_cbranch_scc1 .Lxl34_have
	s_and_saveexec_b64 s[6:7], s[4:5]
	s_cbranch_execz .Lxl34_m1
	v_mov_b32_e32 v0, 0
	global_load_dword v1, v0, s[46:47] offset:1152 sc1
	global_load_dword v2, v0, s[46:47] offset:1408 sc1
	global_load_dword v3, v0, s[46:47] offset:1664 sc1
	global_load_dword v4, v0, s[46:47] offset:1920 sc1
	global_load_dword v5, v0, s[46:47] offset:2176 sc1
	global_load_dword v6, v0, s[46:47] offset:2432 sc1
	global_load_dword v7, v0, s[46:47] offset:2688 sc1
	global_load_dword v8, v0, s[46:47] offset:2944 sc1
	s_waitcnt vmcnt(0)
	v_or3_b32 v9, v1, v2, v3
	v_or3_b32 v9, v9, v4, v5
	v_or3_b32 v9, v9, v6, v7
	v_or_b32_e32 v9, v9, v8
	v_mov_b32_e32 v11, 0
	v_add_u32_e32 v10, -1, v1
	v_and_b32_e32 v10, v10, v1
	v_or_b32_e32 v11, v11, v10
	v_add_u32_e32 v10, -1, v2
	v_and_b32_e32 v10, v10, v2
	v_or_b32_e32 v11, v11, v10
	v_add_u32_e32 v10, -1, v3
	v_and_b32_e32 v10, v10, v3
	v_or_b32_e32 v11, v11, v10
	v_add_u32_e32 v10, -1, v4
	v_and_b32_e32 v10, v10, v4
	v_or_b32_e32 v11, v11, v10
	v_add_u32_e32 v10, -1, v5
	v_and_b32_e32 v10, v10, v5
	v_or_b32_e32 v11, v11, v10
	v_add_u32_e32 v10, -1, v6
	v_and_b32_e32 v10, v10, v6
	v_or_b32_e32 v11, v11, v10
	v_add_u32_e32 v10, -1, v7
	v_and_b32_e32 v10, v10, v7
	v_or_b32_e32 v11, v11, v10
	v_add_u32_e32 v10, -1, v8
	v_and_b32_e32 v10, v10, v8
	v_or_b32_e32 v11, v11, v10
	s_nop 1
	v_readfirstlane_b32 s8, v9
	v_readfirstlane_b32 s9, v11
	s_nop 3
	s_cmp_eq_u32 s8, 0xff
	s_cselect_b32 s11, 1, 0
	s_cmp_eq_u32 s9, 0
	s_cselect_b32 s11, s11, 0
	s_cmp_eq_u32 s52, 0x200
	s_cselect_b32 s11, s11, 0
	s_cmp_eq_u32 s11, 1
	s_cselect_b32 s10, 1, 2
	v_mov_b32_e32 v0, 8
	v_mov_b32_e32 v1, s10
	ds_write_b32 v0, v1
	s_waitcnt lgkmcnt(0)

.Lxl34_orig:
	s_waitcnt vmcnt(0)
	s_waitcnt vmcnt(0) lgkmcnt(0)
	s_barrier
	s_and_saveexec_b64 s[6:7], s[4:5]
	s_cbranch_execz .LBB0_328
	v_mov_b32_e32 v16, 0
	s_waitcnt vmcnt(0) expcnt(0) lgkmcnt(0)
	ds_read_b32 v2, v16
	ds_read_b32 v0, v16 offset:4
	s_waitcnt lgkmcnt(1)
	v_cmp_ne_u32_e32 vcc, 0, v2
	s_cbranch_vccnz .LBB0_292
	s_add_u32 s8, s46, 0x1000
	s_addc_u32 s9, s47, 0
	s_add_u32 s10, s46, 0x1100
	s_addc_u32 s11, s47, 0
	s_add_u32 s12, s46, 0x1200
	s_addc_u32 s13, s47, 0
	s_mul_i32 s3, s53, s78
	s_add_u32 s14, s46, 0x1300
	s_mul_i32 s3, s3, s52
	s_addc_u32 s15, s47, 0
	s_mov_b32 s22, 1
	s_branch .LBB0_280
